# attention tile epilogue: the 8 norm-weight (gamma) loads are issued at K-loop exit into dead K/V fragment registers instead of after the cross-wave reduction barrier
# baseline (speedup 1.0000x reference)
.LBB0_1566:
	s_setprio 0
	s_load_dwordx2 s[98:99], s[0:1], 0x48
	s_lshl_b64 s[100:101], s[6:7], 2
	v_lshlrev_b32_e32 v129, 2, v165
	s_waitcnt lgkmcnt(0)
	s_add_u32 s98, s98, s100
	s_addc_u32 s99, s99, s101
	global_load_dwordx4 v[158:161], v129, s[98:99]
	global_load_dwordx4 v[154:157], v129, s[98:99] offset:32
	global_load_dwordx4 v[150:153], v129, s[98:99] offset:64
	global_load_dwordx4 v[146:149], v129, s[98:99] offset:96
	global_load_dwordx4 v[142:145], v129, s[98:99] offset:128
	global_load_dwordx4 v[138:141], v129, s[98:99] offset:160
	global_load_dwordx4 v[134:137], v129, s[98:99] offset:192
	global_load_dwordx4 v[130:133], v129, s[98:99] offset:224
	v_div_scale_f32 v67, s[2:3], v66, v66, 1.0
	v_rcp_f32_e32 v68, v67
	v_div_scale_f32 v69, vcc, 1.0, v66, 1.0
	s_lshl_b32 s2, s6, 2
	v_fma_f32 v70, -v67, v68, 1.0
	v_fmac_f32_e32 v68, v70, v68
	v_mul_f32_e32 v70, v69, v68
	v_fma_f32 v71, -v67, v70, v69
	v_fmac_f32_e32 v70, v71, v68
	v_fma_f32 v67, -v67, v70, v69
	v_div_fmas_f32 v67, v67, v68, v70
	v_div_fixup_f32 v68, v67, v66, 1.0
	v_pk_mul_f32 v[110:111], v[68:69], v[50:51] op_sel_hi:[0,1]
	v_pk_mul_f32 v[50:51], v[110:111], v[110:111]
	v_pk_mul_f32 v[112:113], v[68:69], v[52:53] op_sel_hi:[0,1]
	v_pk_mul_f32 v[52:53], v[112:113], v[112:113]
	v_add_f32_e32 v50, v50, v51
	v_pk_mul_f32 v[108:109], v[68:69], v[54:55] op_sel_hi:[0,1]
	v_add_f32_e32 v50, v52, v50
	v_pk_mul_f32 v[54:55], v[108:109], v[108:109]
	v_add_f32_e32 v50, v53, v50
	v_pk_mul_f32 v[106:107], v[68:69], v[56:57] op_sel_hi:[0,1]
	v_add_f32_e32 v50, v54, v50
	v_pk_mul_f32 v[56:57], v[106:107], v[106:107]
	v_add_f32_e32 v50, v55, v50
	v_pk_mul_f32 v[104:105], v[68:69], v[58:59] op_sel_hi:[0,1]
	v_add_f32_e32 v50, v56, v50
	v_pk_mul_f32 v[58:59], v[104:105], v[104:105]
	v_add_f32_e32 v50, v57, v50
	v_pk_mul_f32 v[102:103], v[68:69], v[60:61] op_sel_hi:[0,1]
	v_add_f32_e32 v50, v58, v50
	v_pk_mul_f32 v[60:61], v[102:103], v[102:103]
	v_add_f32_e32 v50, v59, v50
	v_pk_mul_f32 v[84:85], v[68:69], v[62:63] op_sel_hi:[0,1]
	v_add_f32_e32 v50, v60, v50
	v_pk_mul_f32 v[62:63], v[84:85], v[84:85]
	v_add_f32_e32 v50, v61, v50
	v_pk_mul_f32 v[82:83], v[68:69], v[64:65] op_sel_hi:[0,1]
	v_add_f32_e32 v50, v62, v50
	v_pk_mul_f32 v[64:65], v[82:83], v[82:83]
	v_add_f32_e32 v50, v63, v50
	v_pk_mul_f32 v[80:81], v[68:69], v[34:35] op_sel_hi:[0,1]
	v_add_f32_e32 v50, v64, v50
	v_pk_mul_f32 v[34:35], v[80:81], v[80:81]
	v_add_f32_e32 v50, v65, v50
	v_pk_mul_f32 v[78:79], v[68:69], v[36:37] op_sel_hi:[0,1]
	v_add_f32_e32 v34, v34, v50
	v_pk_mul_f32 v[36:37], v[78:79], v[78:79]
	v_add_f32_e32 v34, v35, v34
	v_pk_mul_f32 v[76:77], v[68:69], v[38:39] op_sel_hi:[0,1]
	v_add_f32_e32 v34, v36, v34
	v_pk_mul_f32 v[38:39], v[76:77], v[76:77]
	v_add_f32_e32 v34, v37, v34
	v_pk_mul_f32 v[74:75], v[68:69], v[40:41] op_sel_hi:[0,1]
	v_add_f32_e32 v34, v38, v34
	v_pk_mul_f32 v[40:41], v[74:75], v[74:75]
	v_add_f32_e32 v34, v39, v34
	v_pk_mul_f32 v[72:73], v[68:69], v[42:43] op_sel_hi:[0,1]
	v_add_f32_e32 v34, v40, v34
	v_pk_mul_f32 v[42:43], v[72:73], v[72:73]
	v_add_f32_e32 v34, v41, v34
	v_pk_mul_f32 v[70:71], v[68:69], v[44:45] op_sel_hi:[0,1]
	v_add_f32_e32 v34, v42, v34
	v_pk_mul_f32 v[44:45], v[70:71], v[70:71]
	v_add_f32_e32 v34, v43, v34
	v_pk_mul_f32 v[66:67], v[68:69], v[46:47] op_sel_hi:[0,1]
	v_add_f32_e32 v34, v44, v34
	v_pk_mul_f32 v[46:47], v[66:67], v[66:67]
	v_add_f32_e32 v34, v45, v34
	v_pk_mul_f32 v[68:69], v[68:69], v[48:49] op_sel_hi:[0,1]
	v_add_f32_e32 v34, v46, v34
	v_pk_mul_f32 v[48:49], v[68:69], v[68:69]
	v_add_f32_e32 v34, v47, v34
	v_add_f32_e32 v34, v48, v34
	v_add_f32_e32 v34, v49, v34
	ds_bpermute_b32 v35, v99, v34
	s_add_i32 s2, s2, 0
	v_cmp_gt_u32_e64 s[40:41], 32, v173
	v_lshl_add_u32 v87, v172, 2, s2
	s_and_saveexec_b64 s[2:3], s[40:41]
	s_cbranch_execz .LBB0_1568
	s_waitcnt lgkmcnt(0)
	v_add_f32_e32 v34, v34, v35
	ds_write_b32 v87, v34 offset:8320

.LBB0_1570:
	s_or_b64 exec, exec, s[2:3]
	s_waitcnt lgkmcnt(0)
	s_barrier
	s_load_dwordx2 s[2:3], s[0:1], 0x48
	s_lshl_b64 s[6:7], s[6:7], 2
	v_lshl_add_u32 v100, v172, 2, 0
	v_add_u32_e32 v90, 0x2000, v100
	s_waitcnt lgkmcnt(0)
	s_add_u32 s2, s2, s6
	s_addc_u32 s3, s3, s7
	s_add_u32 s2, s23, s4
	s_addc_u32 s3, s24, s5
	v_lshlrev_b64 v[114:115], 11, v[0:1]
	v_lshl_add_u64 v[114:115], s[2:3], 0, v[114:115]
	v_lshlrev_b32_e32 v0, 1, v165
	ds_read2_b32 v[86:87], v90 offset0:32 offset1:64
	ds_read2_b32 v[88:89], v90 offset0:96 offset1:128
	ds_read2_b32 v[90:91], v90 offset0:160 offset1:192
	s_waitcnt lgkmcnt(2)
	v_add_f32_e32 v86, 0, v86
	s_waitcnt lgkmcnt(1)
	v_add_f32_e32 v86, v86, v88
	v_add_u32_e32 v88, 0x2200, v100
	ds_read2_b32 v[92:93], v88 offset0:96 offset1:128
	v_add_u32_e32 v88, 0x2400, v100
	ds_read2_b32 v[94:95], v88 offset0:32 offset1:64
	ds_read2_b32 v[96:97], v88 offset0:96 offset1:128
	ds_read2_b32 v[98:99], v88 offset0:160 offset1:192
	v_add_u32_e32 v88, 0x2600, v100
	s_waitcnt lgkmcnt(4)
	v_add_f32_e32 v86, v86, v90
	ds_read2_b32 v[100:101], v88 offset0:96 offset1:128
	s_waitcnt lgkmcnt(4)
	v_add_f32_e32 v86, v86, v92
	s_waitcnt lgkmcnt(3)
	v_add_f32_e32 v86, v86, v94
	s_waitcnt lgkmcnt(2)
	v_add_f32_e32 v86, v86, v96
	s_waitcnt lgkmcnt(1)
	v_add_f32_e32 v86, v86, v98
	s_waitcnt lgkmcnt(0)
	v_add_f32_e32 v86, v86, v100
	v_fmamk_f32 v86, v86, 0x3b000000, v180
	v_cmp_gt_f32_e32 vcc, s19, v86
	v_mul_f32_e32 v88, 0x4f800000, v86
	s_nop 0
	v_cndmask_b32_e32 v86, v86, v88, vcc
	v_sqrt_f32_e32 v88, v86
	s_nop 0
	v_add_u32_e32 v90, -1, v88
	v_fma_f32 v92, -v90, v88, v86
	v_cmp_ge_f32_e64 s[40:41], 0, v92
	v_add_u32_e32 v92, 1, v88
	s_nop 0
	v_cndmask_b32_e64 v90, v88, v90, s[40:41]
	v_fma_f32 v88, -v92, v88, v86
	v_cmp_lt_f32_e64 s[40:41], 0, v88
	s_nop 1
	v_cndmask_b32_e64 v88, v90, v92, s[40:41]
	v_mul_f32_e32 v90, 0x37800000, v88
	v_cndmask_b32_e32 v88, v88, v90, vcc
	v_cmp_class_f32_e32 vcc, v86, v181
	s_nop 1
	v_cndmask_b32_e32 v86, v88, v86, vcc
	v_div_scale_f32 v88, s[4:5], v86, v86, 1.0
	v_rcp_f32_e32 v90, v88
	s_nop 0
	v_fma_f32 v92, -v88, v90, 1.0
	v_fmac_f32_e32 v90, v92, v90
	v_div_scale_f32 v92, vcc, 1.0, v86, 1.0
	v_mul_f32_e32 v94, v92, v90
	v_fma_f32 v96, -v88, v94, v92
	v_fmac_f32_e32 v94, v96, v90
	v_fma_f32 v88, -v88, v94, v92
	v_div_fmas_f32 v88, v88, v90, v94
	v_div_fixup_f32 v86, v88, v86, 1.0
	v_pk_mul_f32 v[110:111], v[110:111], v[86:87] op_sel_hi:[1,0]
	v_pk_mul_f32 v[66:67], v[66:67], v[86:87] op_sel_hi:[1,0]
	s_waitcnt vmcnt(0)
	v_pk_mul_f32 v[110:111], v[158:159], v[110:111]
	v_pk_mul_f32 v[68:69], v[68:69], v[86:87] op_sel_hi:[1,0]
	v_cvt_pk_bf16_f32 v116, v110, v111
	v_pk_mul_f32 v[110:111], v[112:113], v[86:87] op_sel_hi:[1,0]
	v_pk_mul_f32 v[66:67], v[130:131], v[66:67]
	v_pk_mul_f32 v[110:111], v[160:161], v[110:111]
	v_pk_mul_f32 v[68:69], v[132:133], v[68:69]
	v_cvt_pk_bf16_f32 v117, v110, v111
	v_lshl_add_u64 v[110:111], v[114:115], 0, v[0:1]
	v_cvt_pk_bf16_f32 v66, v66, v67
	v_cvt_pk_bf16_f32 v67, v68, v69
	global_store_dwordx2 v[110:111], v[66:67], off offset:112
	v_add_f32_e32 v66, 0, v87
	v_add_f32_e32 v66, v66, v89
	v_add_f32_e32 v66, v66, v91
	v_add_f32_e32 v66, v66, v93
	v_add_f32_e32 v66, v66, v95
	v_add_f32_e32 v66, v66, v97
	v_add_f32_e32 v66, v66, v99
	v_add_f32_e32 v66, v66, v101
	v_fmamk_f32 v66, v66, 0x3b000000, v180
	v_cmp_gt_f32_e32 vcc, s19, v66
	v_mul_f32_e32 v67, 0x4f800000, v66
	v_pk_mul_f32 v[72:73], v[72:73], v[86:87] op_sel_hi:[1,0]
	v_cndmask_b32_e32 v66, v66, v67, vcc
	v_sqrt_f32_e32 v67, v66
	v_pk_mul_f32 v[70:71], v[70:71], v[86:87] op_sel_hi:[1,0]
	v_pk_mul_f32 v[72:73], v[134:135], v[72:73]
	v_pk_mul_f32 v[70:71], v[136:137], v[70:71]
	v_add_u32_e32 v68, -1, v67
	v_fma_f32 v69, -v68, v67, v66
	v_cmp_ge_f32_e64 s[40:41], 0, v69
	v_add_u32_e32 v69, 1, v67
	v_cvt_pk_bf16_f32 v72, v72, v73
	v_cndmask_b32_e64 v68, v67, v68, s[40:41]
	v_fma_f32 v67, -v69, v67, v66
	v_cmp_lt_f32_e64 s[40:41], 0, v67
	v_cvt_pk_bf16_f32 v73, v70, v71
	v_pk_mul_f32 v[108:109], v[108:109], v[86:87] op_sel_hi:[1,0]
	v_cndmask_b32_e64 v67, v68, v69, s[40:41]
	v_mul_f32_e32 v68, 0x37800000, v67
	v_cndmask_b32_e32 v67, v67, v68, vcc
	v_cmp_class_f32_e32 vcc, v66, v181
	v_pk_mul_f32 v[108:109], v[154:155], v[108:109]
	v_pk_mul_f32 v[106:107], v[106:107], v[86:87] op_sel_hi:[1,0]
	v_cndmask_b32_e32 v66, v67, v66, vcc
	v_div_scale_f32 v67, s[4:5], v66, v66, 1.0
	v_rcp_f32_e32 v68, v67
	v_pk_mul_f32 v[106:107], v[156:157], v[106:107]
	v_pk_mul_f32 v[104:105], v[104:105], v[86:87] op_sel_hi:[1,0]
	v_pk_mul_f32 v[102:103], v[102:103], v[86:87] op_sel_hi:[1,0]
	v_fma_f32 v69, -v67, v68, 1.0
	v_fmac_f32_e32 v68, v69, v68
	v_div_scale_f32 v69, vcc, 1.0, v66, 1.0
	v_mul_f32_e32 v70, v69, v68
	v_fma_f32 v71, -v67, v70, v69
	v_fmac_f32_e32 v70, v71, v68
	v_fma_f32 v67, -v67, v70, v69
	v_div_fmas_f32 v67, v67, v68, v70
	v_div_fixup_f32 v66, v67, v66, 1.0
	v_pk_mul_f32 v[62:63], v[62:63], v[66:67] op_sel_hi:[1,0]
	v_lshlrev_b64 v[68:69], 11, v[162:163]
	v_pk_mul_f32 v[30:31], v[158:159], v[62:63]
	v_pk_mul_f32 v[62:63], v[64:65], v[66:67] op_sel_hi:[1,0]
	v_lshl_add_u64 v[68:69], s[2:3], 0, v[68:69]
	v_pk_mul_f32 v[32:33], v[160:161], v[62:63]
	v_cvt_pk_bf16_f32 v30, v30, v31
	v_cvt_pk_bf16_f32 v31, v32, v33
	v_lshl_add_u64 v[118:119], v[68:69], 0, v[0:1]
	global_store_dwordx2 v[118:119], v[30:31], off
	v_pk_mul_f32 v[30:31], v[56:57], v[66:67] op_sel_hi:[1,0]
	v_pk_mul_f32 v[104:105], v[150:151], v[104:105]
	v_pk_mul_f32 v[26:27], v[154:155], v[30:31]
	v_pk_mul_f32 v[30:31], v[60:61], v[66:67] op_sel_hi:[1,0]
	v_cvt_pk_bf16_f32 v26, v26, v27
	v_pk_mul_f32 v[28:29], v[156:157], v[30:31]
	v_pk_mul_f32 v[102:103], v[152:153], v[102:103]
	v_cvt_pk_bf16_f32 v27, v28, v29
	global_store_dwordx2 v[118:119], v[26:27], off offset:16
	v_pk_mul_f32 v[26:27], v[52:53], v[66:67] op_sel_hi:[1,0]
	v_pk_mul_f32 v[84:85], v[84:85], v[86:87] op_sel_hi:[1,0]
	v_pk_mul_f32 v[22:23], v[150:151], v[26:27]
	v_pk_mul_f32 v[26:27], v[58:59], v[66:67] op_sel_hi:[1,0]
	v_cvt_pk_bf16_f32 v22, v22, v23
	v_pk_mul_f32 v[24:25], v[152:153], v[26:27]
	v_pk_mul_f32 v[84:85], v[146:147], v[84:85]
	v_cvt_pk_bf16_f32 v23, v24, v25
	global_store_dwordx2 v[118:119], v[22:23], off offset:32
	v_pk_mul_f32 v[22:23], v[50:51], v[66:67] op_sel_hi:[1,0]
	v_pk_mul_f32 v[82:83], v[82:83], v[86:87] op_sel_hi:[1,0]
	v_pk_mul_f32 v[18:19], v[146:147], v[22:23]
	v_pk_mul_f32 v[22:23], v[54:55], v[66:67] op_sel_hi:[1,0]
	v_pk_mul_f32 v[82:83], v[148:149], v[82:83]
	v_pk_mul_f32 v[20:21], v[148:149], v[22:23]
	v_cvt_pk_bf16_f32 v18, v18, v19
	v_cvt_pk_bf16_f32 v19, v20, v21
	v_pk_mul_f32 v[80:81], v[80:81], v[86:87] op_sel_hi:[1,0]
	global_store_dwordx2 v[118:119], v[18:19], off offset:48
	v_pk_mul_f32 v[18:19], v[44:45], v[66:67] op_sel_hi:[1,0]
	v_pk_mul_f32 v[80:81], v[142:143], v[80:81]
	v_pk_mul_f32 v[78:79], v[78:79], v[86:87] op_sel_hi:[1,0]
	v_pk_mul_f32 v[14:15], v[142:143], v[18:19]
	v_pk_mul_f32 v[18:19], v[48:49], v[66:67] op_sel_hi:[1,0]
	v_pk_mul_f32 v[78:79], v[144:145], v[78:79]
	v_pk_mul_f32 v[16:17], v[144:145], v[18:19]
	v_cvt_pk_bf16_f32 v14, v14, v15
	v_cvt_pk_bf16_f32 v15, v16, v17
	v_pk_mul_f32 v[76:77], v[76:77], v[86:87] op_sel_hi:[1,0]
	global_store_dwordx2 v[118:119], v[14:15], off offset:64
	v_pk_mul_f32 v[14:15], v[40:41], v[66:67] op_sel_hi:[1,0]
	v_pk_mul_f32 v[76:77], v[138:139], v[76:77]
	v_pk_mul_f32 v[74:75], v[74:75], v[86:87] op_sel_hi:[1,0]
	v_pk_mul_f32 v[10:11], v[138:139], v[14:15]
	v_pk_mul_f32 v[14:15], v[46:47], v[66:67] op_sel_hi:[1,0]
	v_pk_mul_f32 v[74:75], v[140:141], v[74:75]
	v_pk_mul_f32 v[12:13], v[140:141], v[14:15]
	v_cvt_pk_bf16_f32 v10, v10, v11
	v_cvt_pk_bf16_f32 v11, v12, v13
	global_store_dwordx2 v[118:119], v[10:11], off offset:80
	v_pk_mul_f32 v[10:11], v[38:39], v[66:67] op_sel_hi:[1,0]
	v_cvt_pk_bf16_f32 v108, v108, v109
	v_pk_mul_f32 v[6:7], v[134:135], v[10:11]
	v_pk_mul_f32 v[10:11], v[42:43], v[66:67] op_sel_hi:[1,0]
	v_cvt_pk_bf16_f32 v6, v6, v7
	v_pk_mul_f32 v[8:9], v[136:137], v[10:11]
	v_cvt_pk_bf16_f32 v109, v106, v107
	v_cvt_pk_bf16_f32 v7, v8, v9
	global_store_dwordx2 v[118:119], v[6:7], off offset:96
	v_pk_mul_f32 v[6:7], v[36:37], v[66:67] op_sel_hi:[1,0]
	v_cvt_pk_bf16_f32 v104, v104, v105
	v_pk_mul_f32 v[2:3], v[130:131], v[6:7]
	v_cvt_pk_bf16_f32 v105, v102, v103
	v_cvt_pk_bf16_f32 v84, v84, v85
	v_cvt_pk_bf16_f32 v85, v82, v83
	v_cvt_pk_bf16_f32 v80, v80, v81
	v_cvt_pk_bf16_f32 v81, v78, v79
	v_cvt_pk_bf16_f32 v76, v76, v77
	v_cvt_pk_bf16_f32 v77, v74, v75
	v_cvt_pk_bf16_f32 v120, v2, v3
	v_pk_mul_f32 v[2:3], v[34:35], v[66:67] op_sel_hi:[1,0]
	global_store_dwordx2 v[110:111], v[116:117], off
	global_store_dwordx2 v[110:111], v[108:109], off offset:16
	global_store_dwordx2 v[110:111], v[104:105], off offset:32
	global_store_dwordx2 v[110:111], v[84:85], off offset:48
	global_store_dwordx2 v[110:111], v[80:81], off offset:64
	global_store_dwordx2 v[110:111], v[76:77], off offset:80
	global_store_dwordx2 v[110:111], v[72:73], off offset:96
	v_pk_mul_f32 v[122:123], v[132:133], v[2:3]
	s_cbranch_execnz .LBB0_1017
